# v55 + window attention (MODE 1): for unmasked near tiles the 16 T5-bias LUT lookups per QK half are issued together (one base + immediate offsets) instead of 16 serialized lookup-wait rounds
# speedup vs baseline: 1.0013x; 1.0013x over previous
.LBB0_653:
	s_and_b32 s57, s55, 1
	s_cmp_gt_u32 s9, s33
	s_cselect_b64 s[2:3], -1, 0
	s_add_i32 s0, s9, 63
	s_cmp_lt_i32 s0, s51
	s_cselect_b64 s[6:7], -1, 0
	s_or_b64 s[2:3], s[2:3], s[6:7]
	s_and_b64 vcc, exec, s[2:3]
	s_cbranch_vccnz .LBB0_667
	s_mul_i32 s1, s57, 0x4400
	v_add_u32_e32 v174, s1, v170
	ds_read_b128 v[212:215], v174
	ds_read_b128 v[216:219], v174 offset:32
	ds_read_b128 v[220:223], v174 offset:64
	ds_read_b128 v[224:227], v174 offset:96
	ds_read_b128 v[228:231], v174 offset:128
	ds_read_b128 v[236:239], v174 offset:160
	ds_read_b128 v[240:243], v174 offset:192
	ds_read_b128 v[244:247], v174 offset:224
	s_cmp_le_u32 s0, s26
	s_cselect_b64 s[2:3], -1, 0
	s_cmp_ge_i32 s9, s54
	s_cselect_b64 s[6:7], -1, 0
	s_and_b64 s[6:7], s[2:3], s[6:7]
	s_cmp_lt_i32 s0, s29
	s_cselect_b64 s[0:1], -1, 0
	s_and_b64 s[0:1], s[6:7], s[0:1]
	s_mov_b64 s[2:3], -1
	s_waitcnt lgkmcnt(7)
	v_mfma_f32_32x32x16_bf16 v[80:95], v[212:215], v[96:99], 0
	s_waitcnt lgkmcnt(6)
	v_mfma_f32_32x32x16_bf16 v[80:95], v[216:219], v[100:103], v[80:95]
	s_waitcnt lgkmcnt(5)
	v_mfma_f32_32x32x16_bf16 v[80:95], v[220:223], v[104:107], v[80:95]
	s_waitcnt lgkmcnt(4)
	v_mfma_f32_32x32x16_bf16 v[80:95], v[224:227], v[108:111], v[80:95]
	s_waitcnt lgkmcnt(3)
	v_mfma_f32_32x32x16_bf16 v[80:95], v[228:231], v[112:115], v[80:95]
	s_waitcnt lgkmcnt(2)
	v_mfma_f32_32x32x16_bf16 v[80:95], v[236:239], v[116:119], v[80:95]
	s_waitcnt lgkmcnt(1)
	v_mfma_f32_32x32x16_bf16 v[80:95], v[240:243], v[120:123], v[80:95]
	s_waitcnt lgkmcnt(0)
	v_mfma_f32_32x32x16_bf16 v[80:95], v[244:247], v[124:127], v[80:95]
	s_and_b64 vcc, exec, s[0:1]
	s_cbranch_vccnz .LBB0_656
	s_cmp_lg_u32 s6, 0
	s_cbranch_scc1 .LleanW1
	v_add_u32_e32 v0, 55, v171
	v_med3_i32 v2, v0, 0, v164
	v_lshl_add_u32 v2, v2, 2, s34
	v_cmp_gt_u32_e32 vcc, s44, v0
	v_add_u32_e32 v0, 54, v171
	ds_read_b32 v2, v2
	v_med3_i32 v3, v0, 0, v164
	v_lshl_add_u32 v3, v3, 2, s34
	v_add_u32_e32 v4, 53, v171
	ds_read_b32 v3, v3
	v_med3_i32 v5, v4, 0, v164
	v_lshl_add_u32 v5, v5, 2, s34
	ds_read_b32 v5, v5
	s_waitcnt lgkmcnt(2)
	v_add_f32_e32 v2, v80, v2
	s_or_b64 vcc, vcc, s[6:7]
	v_cndmask_b32_e32 v2, v162, v2, vcc
	v_cmp_gt_u32_e32 vcc, s44, v0
	s_waitcnt lgkmcnt(1)
	v_add_f32_e32 v3, v81, v3
	s_or_b64 vcc, s[6:7], vcc
	v_cndmask_b32_e32 v3, v162, v3, vcc
	v_cmp_gt_u32_e32 vcc, s44, v4
	s_waitcnt lgkmcnt(0)
	v_add_f32_e32 v5, v82, v5
	s_or_b64 vcc, s[6:7], vcc
	v_cndmask_b32_e32 v4, v162, v5, vcc
	v_add_u32_e32 v5, 52, v171
	v_med3_i32 v6, v5, 0, v164
	v_lshl_add_u32 v6, v6, 2, s34
	ds_read_b32 v6, v6
	v_cmp_gt_u32_e32 vcc, s44, v5
	s_or_b64 vcc, s[6:7], vcc
	v_max3_f32 v0, v2, s47, v3
	s_mov_b64 s[2:3], 0
	s_waitcnt lgkmcnt(0)
	v_add_f32_e32 v6, v83, v6
	v_cndmask_b32_e32 v5, v162, v6, vcc
	v_add_u32_e32 v6, 51, v171
	v_med3_i32 v7, v6, 0, v164
	v_lshl_add_u32 v7, v7, 2, s34
	ds_read_b32 v7, v7
	v_cmp_gt_u32_e32 vcc, s44, v6
	s_or_b64 vcc, s[6:7], vcc
	v_max3_f32 v0, v0, v4, v5
	s_waitcnt lgkmcnt(0)
	v_add_f32_e32 v7, v84, v7
	v_cndmask_b32_e32 v6, v162, v7, vcc
	v_add_u32_e32 v7, 50, v171
	v_med3_i32 v8, v7, 0, v164
	v_lshl_add_u32 v8, v8, 2, s34
	ds_read_b32 v8, v8
	v_cmp_gt_u32_e32 vcc, s44, v7
	s_or_b64 vcc, s[6:7], vcc
	s_waitcnt lgkmcnt(0)
	v_add_f32_e32 v8, v85, v8
	v_cndmask_b32_e32 v7, v162, v8, vcc
	v_add_u32_e32 v8, 49, v171
	v_med3_i32 v9, v8, 0, v164
	v_lshl_add_u32 v9, v9, 2, s34
	ds_read_b32 v9, v9
	v_cmp_gt_u32_e32 vcc, s44, v8
	s_or_b64 vcc, s[6:7], vcc
	v_max3_f32 v0, v0, v6, v7
	s_waitcnt lgkmcnt(0)
	v_add_f32_e32 v9, v86, v9
	v_cndmask_b32_e32 v8, v162, v9, vcc
	v_add_u32_e32 v9, 48, v171
	v_med3_i32 v10, v9, 0, v164
	v_lshl_add_u32 v10, v10, 2, s34
	ds_read_b32 v10, v10
	v_cmp_gt_u32_e32 vcc, s44, v9
	s_or_b64 vcc, s[6:7], vcc
	s_waitcnt lgkmcnt(0)
	v_add_f32_e32 v10, v87, v10
	v_cndmask_b32_e32 v9, v162, v10, vcc
	v_add_u32_e32 v10, 39, v171
	v_med3_i32 v11, v10, 0, v164
	v_lshl_add_u32 v11, v11, 2, s34
	ds_read_b32 v11, v11
	v_cmp_gt_u32_e32 vcc, s44, v10
	s_or_b64 vcc, vcc, s[6:7]
	v_max3_f32 v0, v0, v8, v9
	s_waitcnt lgkmcnt(0)
	v_add_f32_e32 v11, v88, v11
	v_cndmask_b32_e32 v10, v162, v11, vcc
	v_add_u32_e32 v11, 38, v171
	v_med3_i32 v12, v11, 0, v164
	v_lshl_add_u32 v12, v12, 2, s34
	ds_read_b32 v12, v12
	v_cmp_gt_u32_e32 vcc, s44, v11
	s_or_b64 vcc, s[6:7], vcc
	s_waitcnt lgkmcnt(0)
	v_add_f32_e32 v12, v89, v12
	v_cndmask_b32_e32 v11, v162, v12, vcc
	v_add_u32_e32 v12, 37, v171
	v_med3_i32 v13, v12, 0, v164
	v_lshl_add_u32 v13, v13, 2, s34
	ds_read_b32 v13, v13
	v_cmp_gt_u32_e32 vcc, s44, v12
	s_or_b64 vcc, s[6:7], vcc
	v_max3_f32 v0, v0, v10, v11
	s_waitcnt lgkmcnt(0)
	v_add_f32_e32 v13, v90, v13
	v_cndmask_b32_e32 v12, v162, v13, vcc
	v_add_u32_e32 v13, 36, v171
	v_med3_i32 v14, v13, 0, v164
	v_lshl_add_u32 v14, v14, 2, s34
	ds_read_b32 v14, v14
	v_cmp_gt_u32_e32 vcc, s44, v13
	s_or_b64 vcc, s[6:7], vcc
	s_waitcnt lgkmcnt(0)
	v_add_f32_e32 v14, v91, v14
	v_cndmask_b32_e32 v13, v162, v14, vcc
	v_add_u32_e32 v14, 35, v171
	v_med3_i32 v15, v14, 0, v164
	v_lshl_add_u32 v15, v15, 2, s34
	ds_read_b32 v15, v15
	v_cmp_gt_u32_e32 vcc, s44, v14
	s_or_b64 vcc, s[6:7], vcc
	v_max3_f32 v0, v0, v12, v13
	s_waitcnt lgkmcnt(0)
	v_add_f32_e32 v15, v92, v15
	v_cndmask_b32_e32 v14, v162, v15, vcc
	v_add_u32_e32 v15, 34, v171
	v_med3_i32 v156, v15, 0, v164
	v_lshl_add_u32 v156, v156, 2, s34
	ds_read_b32 v156, v156
	v_cmp_gt_u32_e32 vcc, s44, v15
	s_or_b64 vcc, s[6:7], vcc
	s_waitcnt lgkmcnt(0)
	v_add_f32_e32 v156, v93, v156
	v_cndmask_b32_e32 v15, v162, v156, vcc
	v_add_u32_e32 v156, 33, v171
	v_med3_i32 v157, v156, 0, v164
	v_lshl_add_u32 v157, v157, 2, s34
	ds_read_b32 v157, v157
	v_cmp_gt_u32_e32 vcc, s44, v156
	s_or_b64 vcc, s[6:7], vcc
	v_max3_f32 v0, v0, v14, v15
	s_waitcnt lgkmcnt(0)
	v_add_f32_e32 v157, v94, v157
	v_cndmask_b32_e32 v156, v162, v157, vcc
	v_add_u32_e32 v157, 32, v171
	v_med3_i32 v175, v157, 0, v164
	v_lshl_add_u32 v175, v175, 2, s34
	ds_read_b32 v175, v175
	v_cmp_gt_u32_e32 vcc, s44, v157
	s_or_b64 vcc, s[6:7], vcc
	s_waitcnt lgkmcnt(0)
	v_add_f32_e32 v175, v95, v175
	v_cndmask_b32_e32 v157, v162, v175, vcc
	v_max3_f32 v0, v0, v156, v157
.LjoinW1:
.LBB0_656:
	s_andn2_b64 vcc, exec, s[2:3]
	s_cbranch_vccnz .LBB0_658
	v_mov_b32_e32 v0, s34
	ds_read_b32 v0, v0 offset:2044
	s_waitcnt lgkmcnt(0)
	s_nop 4
	v_pk_add_f32 v[2:3], v[80:81], v[0:1] op_sel_hi:[1,0]
	v_pk_add_f32 v[4:5], v[82:83], v[0:1] op_sel_hi:[1,0]
	v_max3_f32 v12, v2, s47, v3
	v_pk_add_f32 v[6:7], v[84:85], v[0:1] op_sel_hi:[1,0]
	v_max3_f32 v12, v12, v4, v5
	v_pk_add_f32 v[8:9], v[86:87], v[0:1] op_sel_hi:[1,0]
	v_max3_f32 v12, v12, v6, v7
	v_pk_add_f32 v[10:11], v[88:89], v[0:1] op_sel_hi:[1,0]
	v_max3_f32 v12, v12, v8, v9
	v_max3_f32 v14, v12, v10, v11
	v_pk_add_f32 v[12:13], v[90:91], v[0:1] op_sel_hi:[1,0]
	v_pk_add_f32 v[156:157], v[94:95], v[0:1] op_sel_hi:[1,0]
	v_max3_f32 v80, v14, v12, v13
	v_pk_add_f32 v[14:15], v[92:93], v[0:1] op_sel_hi:[1,0]
	s_nop 0
	v_max3_f32 v80, v80, v14, v15
	v_max3_f32 v0, v80, v156, v157

.LleanW1:
	s_mov_b64 s[2:3], 0
	v_lshl_add_u32 v196, v171, 2, s34
	ds_read_b32 v197, v196 offset:220
	ds_read_b32 v198, v196 offset:216
	ds_read_b32 v200, v196 offset:212
	ds_read_b32 v201, v196 offset:208
	ds_read_b32 v202, v196 offset:204
	ds_read_b32 v203, v196 offset:200
	ds_read_b32 v204, v196 offset:196
	ds_read_b32 v205, v196 offset:192
	ds_read_b32 v206, v196 offset:156
	ds_read_b32 v207, v196 offset:152
	ds_read_b32 v208, v196 offset:148
	ds_read_b32 v209, v196 offset:144
	ds_read_b32 v210, v196 offset:140
	ds_read_b32 v211, v196 offset:136
	ds_read_b32 v232, v196 offset:132
	ds_read_b32 v233, v196 offset:128
	s_waitcnt lgkmcnt(0)
	v_add_f32_e32 v2, v80, v197
	v_add_f32_e32 v3, v81, v198
	v_add_f32_e32 v4, v82, v200
	v_max3_f32 v0, v2, s47, v3
	v_add_f32_e32 v5, v83, v201
	v_max3_f32 v0, v0, v4, v5
	v_add_f32_e32 v6, v84, v202
	v_add_f32_e32 v7, v85, v203
	v_max3_f32 v0, v0, v6, v7
	v_add_f32_e32 v8, v86, v204
	v_add_f32_e32 v9, v87, v205
	v_max3_f32 v0, v0, v8, v9
	v_add_f32_e32 v10, v88, v206
	v_add_f32_e32 v11, v89, v207
	v_max3_f32 v0, v0, v10, v11
	v_add_f32_e32 v12, v90, v208
	v_add_f32_e32 v13, v91, v209
	v_max3_f32 v0, v0, v12, v13
	v_add_f32_e32 v14, v92, v210
	v_add_f32_e32 v15, v93, v211
	v_max3_f32 v0, v0, v14, v15
	v_add_f32_e32 v156, v94, v232
	v_add_f32_e32 v157, v95, v233
	v_max3_f32 v0, v0, v156, v157
	s_branch .LjoinW1
.LleanW2:
	s_mov_b64 s[0:1], 0
	v_lshl_add_u32 v196, v171, 2, s34
	ds_read_b32 v197, v196 offset:92
	ds_read_b32 v198, v196 offset:88
	ds_read_b32 v200, v196 offset:84
	ds_read_b32 v201, v196 offset:80
	ds_read_b32 v202, v196 offset:76
	ds_read_b32 v203, v196 offset:72
	ds_read_b32 v204, v196 offset:68
	ds_read_b32 v205, v196 offset:64
	ds_read_b32 v206, v196 offset:28
	ds_read_b32 v207, v196 offset:24
	ds_read_b32 v208, v196 offset:20
	ds_read_b32 v209, v196 offset:16
	ds_read_b32 v210, v196 offset:12
	ds_read_b32 v211, v196 offset:8
	ds_read_b32 v232, v196 offset:4
	ds_read_b32 v233, v196 offset:0
	s_waitcnt lgkmcnt(0)
	v_add_f32_e32 v2, v80, v197
	v_add_f32_e32 v3, v81, v198
	v_max3_f32 v6, v2, s47, v3
	v_add_f32_e32 v4, v82, v200
	v_add_f32_e32 v5, v83, v201
	v_max3_f32 v8, v6, v4, v5
	v_add_f32_e32 v6, v84, v202
	v_add_f32_e32 v7, v85, v203
	v_max3_f32 v10, v8, v6, v7
	v_add_f32_e32 v8, v86, v204
	v_add_f32_e32 v9, v87, v205
	v_max3_f32 v12, v10, v8, v9
	v_add_f32_e32 v10, v88, v206
	v_add_f32_e32 v11, v89, v207
	v_max3_f32 v14, v12, v10, v11
	v_add_f32_e32 v12, v90, v208
	v_add_f32_e32 v13, v91, v209
	v_max3_f32 v156, v14, v12, v13
	v_add_f32_e32 v14, v92, v210
	v_add_f32_e32 v15, v93, v211
	v_max3_f32 v174, v156, v14, v15
	v_add_f32_e32 v156, v94, v232
	v_add_f32_e32 v157, v95, v233
	v_max3_f32 v174, v174, v156, v157
	s_branch .LjoinW2

.Ljoin660:
	v_cvt_pk_bf16_f32 v2, v175, v176
	v_cvt_pk_bf16_f32 v3, v177, v178
	v_cvt_pk_bf16_f32 v4, v179, v180
	v_cvt_pk_bf16_f32 v5, v181, v183
	v_cvt_pk_bf16_f32 v6, v184, v185
	v_cvt_pk_bf16_f32 v7, v186, v187
	v_cvt_pk_bf16_f32 v8, v188, v189
	v_cvt_pk_bf16_f32 v9, v190, v191
	s_mul_i32 s2, s57, 0x4800
	v_add_u32_e32 v0, s2, v169
	ds_read_b128 v[212:215], v0 offset:34816
	ds_read_b128 v[216:219], v0 offset:34848
	ds_read_b128 v[220:223], v0 offset:39424
	ds_read_b128 v[224:227], v0 offset:39456
	ds_read_b128 v[228:231], v0 offset:44032
	ds_read_b128 v[236:239], v0 offset:44064
	ds_read_b128 v[240:243], v0 offset:48640
	ds_read_b128 v[244:247], v0 offset:48672
	s_waitcnt lgkmcnt(7)
	v_mfma_f32_32x32x16_bf16 v[64:79], v[212:215], v[2:5], v[64:79]
	s_waitcnt lgkmcnt(6)
	v_mfma_f32_32x32x16_bf16 v[64:79], v[216:219], v[6:9], v[64:79]
	s_waitcnt lgkmcnt(5)
	v_mfma_f32_32x32x16_bf16 v[48:63], v[220:223], v[2:5], v[48:63]
	s_waitcnt lgkmcnt(4)
	v_mfma_f32_32x32x16_bf16 v[48:63], v[224:227], v[6:9], v[48:63]
	s_waitcnt lgkmcnt(3)
	v_mfma_f32_32x32x16_bf16 v[32:47], v[228:231], v[2:5], v[32:47]
	s_waitcnt lgkmcnt(2)
	v_mfma_f32_32x32x16_bf16 v[32:47], v[236:239], v[6:9], v[32:47]
	s_waitcnt lgkmcnt(1)
	v_mfma_f32_32x32x16_bf16 v[16:31], v[240:243], v[2:5], v[16:31]
	s_waitcnt lgkmcnt(0)
	v_mfma_f32_32x32x16_bf16 v[16:31], v[244:247], v[6:9], v[16:31]
	ds_read_b128 v[212:215], v174 offset:8704
	ds_read_b128 v[216:219], v174 offset:8736
	ds_read_b128 v[220:223], v174 offset:8768
	ds_read_b128 v[224:227], v174 offset:8800
	ds_read_b128 v[228:231], v174 offset:8832
	ds_read_b128 v[236:239], v174 offset:8864
	ds_read_b128 v[240:243], v174 offset:8896
	ds_read_b128 v[244:247], v174 offset:8928
	s_waitcnt lgkmcnt(7)
	v_mfma_f32_32x32x16_bf16 v[80:95], v[212:215], v[96:99], 0
	s_waitcnt lgkmcnt(6)
	v_mfma_f32_32x32x16_bf16 v[80:95], v[216:219], v[100:103], v[80:95]
	s_waitcnt lgkmcnt(5)
	v_mfma_f32_32x32x16_bf16 v[80:95], v[220:223], v[104:107], v[80:95]
	s_waitcnt lgkmcnt(4)
	v_mfma_f32_32x32x16_bf16 v[80:95], v[224:227], v[108:111], v[80:95]
	s_waitcnt lgkmcnt(3)
	v_mfma_f32_32x32x16_bf16 v[80:95], v[228:231], v[112:115], v[80:95]
	s_waitcnt lgkmcnt(2)
	v_mfma_f32_32x32x16_bf16 v[80:95], v[236:239], v[116:119], v[80:95]
	s_waitcnt lgkmcnt(1)
	v_mfma_f32_32x32x16_bf16 v[80:95], v[240:243], v[120:123], v[80:95]
	s_waitcnt lgkmcnt(0)
	v_mfma_f32_32x32x16_bf16 v[80:95], v[244:247], v[124:127], v[80:95]
	s_andn2_b64 vcc, exec, s[0:1]
	s_mov_b64 s[0:1], -1
	s_cbranch_vccnz .LBB0_662
	s_cmp_lg_u32 s6, 0
	s_cbranch_scc1 .LleanW2
	v_add_u32_e32 v2, 23, v171
	v_med3_i32 v3, v2, 0, v164
	v_lshl_add_u32 v3, v3, 2, s34
	ds_read_b32 v3, v3
	v_cmp_gt_u32_e32 vcc, s44, v2
	s_or_b64 vcc, vcc, s[6:7]
	s_mov_b64 s[0:1], 0
	s_waitcnt lgkmcnt(0)
	s_nop 0
	v_add_f32_e32 v3, v80, v3
	v_cndmask_b32_e32 v2, v162, v3, vcc
	v_add_u32_e32 v3, 22, v171
	v_med3_i32 v4, v3, 0, v164
	v_lshl_add_u32 v4, v4, 2, s34
	ds_read_b32 v4, v4
	v_cmp_gt_u32_e32 vcc, s44, v3
	s_or_b64 vcc, s[6:7], vcc
	s_waitcnt lgkmcnt(0)
	v_add_f32_e32 v4, v81, v4
	v_cndmask_b32_e32 v3, v162, v4, vcc
	v_add_u32_e32 v4, 21, v171
	v_med3_i32 v5, v4, 0, v164
	v_lshl_add_u32 v5, v5, 2, s34
	ds_read_b32 v5, v5
	v_cmp_gt_u32_e32 vcc, s44, v4
	s_or_b64 vcc, s[6:7], vcc
	v_max3_f32 v6, v2, s47, v3
	s_waitcnt lgkmcnt(0)
	v_add_f32_e32 v5, v82, v5
	v_cndmask_b32_e32 v4, v162, v5, vcc
	v_add_u32_e32 v5, 20, v171
	v_med3_i32 v7, v5, 0, v164
	v_lshl_add_u32 v7, v7, 2, s34
	ds_read_b32 v7, v7
	v_cmp_gt_u32_e32 vcc, s44, v5
	s_or_b64 vcc, s[6:7], vcc
	s_waitcnt lgkmcnt(0)
	v_add_f32_e32 v7, v83, v7
	v_cndmask_b32_e32 v5, v162, v7, vcc
	v_max3_f32 v8, v6, v4, v5
	v_add_u32_e32 v6, 19, v171
	v_med3_i32 v7, v6, 0, v164
	v_lshl_add_u32 v7, v7, 2, s34
	ds_read_b32 v7, v7
	v_cmp_gt_u32_e32 vcc, s44, v6
	s_or_b64 vcc, s[6:7], vcc
	s_waitcnt lgkmcnt(0)
	v_add_f32_e32 v7, v84, v7
	v_cndmask_b32_e32 v6, v162, v7, vcc
	v_add_u32_e32 v7, 18, v171
	v_med3_i32 v9, v7, 0, v164
	v_lshl_add_u32 v9, v9, 2, s34
	ds_read_b32 v9, v9
	v_cmp_gt_u32_e32 vcc, s44, v7
	s_or_b64 vcc, s[6:7], vcc
	s_waitcnt lgkmcnt(0)
	v_add_f32_e32 v9, v85, v9
	v_cndmask_b32_e32 v7, v162, v9, vcc
	v_max3_f32 v10, v8, v6, v7
	v_add_u32_e32 v8, 17, v171
	v_med3_i32 v9, v8, 0, v164
	v_lshl_add_u32 v9, v9, 2, s34
	ds_read_b32 v9, v9
	v_cmp_gt_u32_e32 vcc, s44, v8
	s_or_b64 vcc, s[6:7], vcc
	s_waitcnt lgkmcnt(0)
	v_add_f32_e32 v9, v86, v9
	v_cndmask_b32_e32 v8, v162, v9, vcc
	v_add_u32_e32 v9, 16, v171
	v_med3_i32 v11, v9, 0, v164
	v_lshl_add_u32 v11, v11, 2, s34
	ds_read_b32 v11, v11
	v_cmp_gt_u32_e32 vcc, s44, v9
	s_or_b64 vcc, s[6:7], vcc
	s_waitcnt lgkmcnt(0)
	v_add_f32_e32 v11, v87, v11
	v_cndmask_b32_e32 v9, v162, v11, vcc
	v_max3_f32 v12, v10, v8, v9
	v_add_u32_e32 v10, 7, v171
	v_med3_i32 v11, v10, 0, v164
	v_lshl_add_u32 v11, v11, 2, s34
	ds_read_b32 v11, v11
	v_cmp_gt_u32_e32 vcc, s44, v10
	s_or_b64 vcc, vcc, s[6:7]
	s_waitcnt lgkmcnt(0)
	v_add_f32_e32 v11, v88, v11
	v_cndmask_b32_e32 v10, v162, v11, vcc
	v_add_u32_e32 v11, 6, v171
	v_med3_i32 v13, v11, 0, v164
	v_lshl_add_u32 v13, v13, 2, s34
	ds_read_b32 v13, v13
	v_cmp_gt_u32_e32 vcc, s44, v11
	s_or_b64 vcc, s[6:7], vcc
	s_waitcnt lgkmcnt(0)
	v_add_f32_e32 v13, v89, v13
	v_cndmask_b32_e32 v11, v162, v13, vcc
	v_max3_f32 v14, v12, v10, v11
	v_add_u32_e32 v12, 5, v171
	v_med3_i32 v13, v12, 0, v164
	v_lshl_add_u32 v13, v13, 2, s34
	ds_read_b32 v13, v13
	v_cmp_gt_u32_e32 vcc, s44, v12
	s_or_b64 vcc, s[6:7], vcc
	s_waitcnt lgkmcnt(0)
	v_add_f32_e32 v13, v90, v13
	v_cndmask_b32_e32 v12, v162, v13, vcc
	v_add_u32_e32 v13, 4, v171
	v_med3_i32 v15, v13, 0, v164
	v_lshl_add_u32 v15, v15, 2, s34
	ds_read_b32 v15, v15
	v_cmp_gt_u32_e32 vcc, s44, v13
	s_or_b64 vcc, s[6:7], vcc
	s_waitcnt lgkmcnt(0)
	v_add_f32_e32 v15, v91, v15
	v_cndmask_b32_e32 v13, v162, v15, vcc
	v_max3_f32 v156, v14, v12, v13
	v_add_u32_e32 v14, 3, v171
	v_med3_i32 v15, v14, 0, v164
	v_lshl_add_u32 v15, v15, 2, s34
	ds_read_b32 v15, v15
	v_cmp_gt_u32_e32 vcc, s44, v14
	s_or_b64 vcc, s[6:7], vcc
	s_waitcnt lgkmcnt(0)
	v_add_f32_e32 v15, v92, v15
	v_cndmask_b32_e32 v14, v162, v15, vcc
	v_add_u32_e32 v15, 2, v171
	v_med3_i32 v157, v15, 0, v164
	v_lshl_add_u32 v157, v157, 2, s34
	ds_read_b32 v157, v157
	v_cmp_gt_u32_e32 vcc, s44, v15
	s_or_b64 vcc, s[6:7], vcc
	s_waitcnt lgkmcnt(0)
	v_add_f32_e32 v157, v93, v157
	v_cndmask_b32_e32 v15, v162, v157, vcc
	v_max3_f32 v174, v156, v14, v15
	v_add_u32_e32 v156, 1, v171
	v_med3_i32 v157, v156, 0, v164
	v_lshl_add_u32 v157, v157, 2, s34
	ds_read_b32 v157, v157
	v_cmp_gt_u32_e32 vcc, s44, v156
	s_or_b64 vcc, s[6:7], vcc
	s_waitcnt lgkmcnt(0)
	v_add_f32_e32 v157, v94, v157
	v_cndmask_b32_e32 v156, v162, v157, vcc
	v_med3_i32 v157, v171, 0, v164
	v_lshl_add_u32 v157, v157, 2, s34
	ds_read_b32 v157, v157
	v_cmp_gt_u32_e32 vcc, s44, v171
	s_or_b64 vcc, s[6:7], vcc
	s_waitcnt lgkmcnt(0)
	v_add_f32_e32 v157, v95, v157
	v_cndmask_b32_e32 v157, v162, v157, vcc
	v_max3_f32 v174, v174, v156, v157
.LjoinW2:
.LBB0_662:
	s_andn2_b64 vcc, exec, s[0:1]
	s_cbranch_vccnz .LBB0_664
	v_mov_b32_e32 v2, s34
	ds_read_b32 v156, v2 offset:2044
	s_waitcnt lgkmcnt(0)
	s_nop 3
	v_pk_add_f32 v[2:3], v[80:81], v[156:157] op_sel_hi:[1,0]
	v_pk_add_f32 v[4:5], v[82:83], v[156:157] op_sel_hi:[1,0]
	v_max3_f32 v12, v2, s47, v3
	v_pk_add_f32 v[6:7], v[84:85], v[156:157] op_sel_hi:[1,0]
	v_max3_f32 v12, v12, v4, v5
	v_pk_add_f32 v[8:9], v[86:87], v[156:157] op_sel_hi:[1,0]
	v_max3_f32 v12, v12, v6, v7
	v_pk_add_f32 v[10:11], v[88:89], v[156:157] op_sel_hi:[1,0]
	v_max3_f32 v12, v12, v8, v9
	v_max3_f32 v14, v12, v10, v11
	v_pk_add_f32 v[12:13], v[90:91], v[156:157] op_sel_hi:[1,0]
	s_nop 0
	v_max3_f32 v80, v14, v12, v13
	v_pk_add_f32 v[14:15], v[92:93], v[156:157] op_sel_hi:[1,0]
	v_pk_add_f32 v[156:157], v[94:95], v[156:157] op_sel_hi:[1,0]
	v_max3_f32 v80, v80, v14, v15
	v_max3_f32 v174, v80, v156, v157
